# also re-touch w_down slice before P5 and w_ple_gate slice + E_raw tile before P6 from idle waves in the hand-off waits
# baseline (speedup 1.0000x reference)
.LBB0_653:
	s_add_u32 s26, s6, 0x8000
	v_readlane_b32 s36, v251, 6
	s_addc_u32 s27, s7, 0
	v_readlane_b32 s50, v251, 20
	v_readlane_b32 s51, v251, 21
	s_add_u32 s16, s50, 0x28200
	s_addc_u32 s17, s51, 0
	s_add_u32 s24, s50, 0x2300000
	s_addc_u32 s25, s51, 0
	s_add_u32 s14, s50, 0x3000000
	s_addc_u32 s15, s51, 0
	s_add_u32 s12, s50, 0x3300000
	s_addc_u32 s13, s51, 0
	s_add_u32 s18, s50, 0xf800000
	s_addc_u32 s19, s51, 0
	s_add_u32 s10, s50, 0x3500000
	s_addc_u32 s11, s51, 0
	s_cmp_lt_i32 s72, 6
	s_cselect_b64 s[2:3], -1, 0
	s_cmp_gt_i32 s73, 5
	s_cselect_b64 s[4:5], -1, 0
	s_and_b64 s[2:3], s[2:3], s[4:5]
	s_andn2_b64 vcc, exec, s[2:3]
	v_readlane_b32 s37, v251, 7
	v_readlane_b32 s38, v251, 8
	v_readlane_b32 s39, v251, 9
	v_readlane_b32 s40, v251, 10
	v_readlane_b32 s41, v251, 11
	v_readlane_b32 s42, v251, 12
	v_readlane_b32 s43, v251, 13
	v_readlane_b32 s44, v251, 14
	v_readlane_b32 s45, v251, 15
	v_readlane_b32 s46, v251, 16
	v_readlane_b32 s47, v251, 17
	v_readlane_b32 s48, v251, 18
	v_readlane_b32 s49, v251, 19
	s_cbranch_vccnz .LBB0_732
	v_readfirstlane_b32 s98, v0
	s_cmp_lt_u32 s98, 64
	s_cbranch_scc1 .Lmy_t5_skip
	v_readlane_b32 s98, v251, 20
	v_readlane_b32 s99, v251, 21
	s_lshl_b32 s100, s70, 15
	s_add_u32 s100, s100, 0x1200000
	s_add_u32 s98, s98, s100
	s_addc_u32 s99, s99, 0
	v_add_u32_e32 v252, 0xffffffc0, v0
	v_lshlrev_b32_e32 v252, 6, v252
	s_nop 1
	global_load_dword v255, v252, s[98:99]
	v_add_u32_e32 v253, 0x7000, v252
	global_load_dword v255, v253, s[98:99]
.Lmy_t5_skip:
	v_cmp_gt_u32_e64 s[2:3], 64, v0
	s_and_saveexec_b64 s[4:5], s[2:3]
	s_cbranch_execz .LBB0_666
	s_memrealtime s[6:7]
	v_mov_b32_e32 v4, 0
	v_mov_b64_e32 v[2:3], 0x1e8481
	s_branch .LBB0_658

.LBB0_732:
	s_cmp_lt_i32 s72, 7
	s_cselect_b64 s[2:3], -1, 0
	s_cmp_gt_i32 s73, 6
	s_cselect_b64 s[4:5], -1, 0
	s_and_b64 s[2:3], s[2:3], s[4:5]
	s_andn2_b64 vcc, exec, s[2:3]
	s_cbranch_vccnz .LBB0_783
	v_readfirstlane_b32 s98, v0
	s_cmp_lt_u32 s98, 256
	s_cbranch_scc1 .Lmy_t6_skip
	v_readlane_b32 s98, v251, 20
	v_readlane_b32 s99, v251, 21
	s_lshl_b32 s100, s70, 13
	s_add_u32 s100, s100, 0x1a00000
	s_add_u32 s100, s98, s100
	s_addc_u32 s101, s99, 0
	v_add_u32_e32 v252, 0xffffff00, v0
	v_lshlrev_b32_e32 v253, 6, v252
	v_and_b32_e32 v253, 0x1fc0, v253
	s_nop 1
	global_load_dword v255, v253, s[100:101]
	s_lshr_b32 s100, s70, 3
	s_and_b32 s100, s100, 7
	s_and_b32 s101, s70, 7
	s_lshl_b32 s101, s101, 3
	s_or_b32 s100, s100, s101
	s_lshl_b32 s100, s100, 19
	s_lshr_b32 s101, s70, 6
	s_lshl_b32 s101, s101, 9
	s_or_b32 s100, s100, s101
	s_add_u32 s100, s100, 0x11800000
	s_add_u32 s98, s98, s100
	s_addc_u32 s99, s99, 0
	v_and_b32_e32 v253, 0xf8, v252
	v_and_b32_e32 v254, 7, v252
	v_lshlrev_b32_e32 v253, 8, v253
	v_lshl_or_b32 v253, v254, 6, v253
	s_nop 1
	global_load_dword v255, v253, s[98:99]
	v_add_u32_e32 v253, 0x10000, v253
	global_load_dword v255, v253, s[98:99]
	v_add_u32_e32 v253, 0x10000, v253
	global_load_dword v255, v253, s[98:99]
	v_add_u32_e32 v253, 0x10000, v253
	global_load_dword v255, v253, s[98:99]
	v_add_u32_e32 v253, 0x10000, v253
	global_load_dword v255, v253, s[98:99]
	v_add_u32_e32 v253, 0x10000, v253
	global_load_dword v255, v253, s[98:99]
	v_add_u32_e32 v253, 0x10000, v253
	global_load_dword v255, v253, s[98:99]
	v_add_u32_e32 v253, 0x10000, v253
	global_load_dword v255, v253, s[98:99]
